# widen P6 final-norm output stores to whole cache lines (dpp row_ror:8 exchange), dpp gate scans in chain prologue
# speedup vs baseline: 1.0480x; 1.0058x over previous
; __device__ __forceinline__ void mlstm_chain(const Params& p, LAS unsigned char* lds, const MlChain ch) {
;     ...
;     for (int cc = wave; cc < nchunks; cc += 8) {
;         const int tok = cc * 64 + lane;
;         float ig = -INFINITY, lf = 0.f;
;         if (tok < T) { const float* gp = GATES + (size_t)(rowbase + tok) * 16; ig = gp[h]; const float f = gp[8 + h]; lf = fminf(f, 0.f) - log1pf(__expf(-fabsf(f))); }
;         float bc = lf;
; #pragma unroll
;         for (int o = 1; o < 64; o <<= 1) { const float t = __shfl_up(bc, o); if (lane >= o) bc += t; }
;         const float u = ig - bc;
;         float cm = u;
; #pragma unroll
;         for (int o = 1; o < 64; o <<= 1) { const float t = __shfl_up(cm, o); if (lane >= o) cm = fmaxf(cm, t); }
;         const float bend = __shfl(bc, 63);
;         const float gmax = wave_max(bend + u);
;         CBC[cc * 64 + lane] = bc; CUU[cc * 64 + lane] = u; CCM[cc * 64 + lane] = cm;
;         if (lane == 0) { CBE[cc] = bend; CGM[cc] = gmax; }
;     }
.LBB0_202:
	v_ashrrev_i32_e32 v51, 31, v50
	s_waitcnt lgkmcnt(1)
	v_lshlrev_b64 v[70:71], 6, v[50:51]
	v_lshl_add_u64 v[70:71], s[20:21], 0, v[70:71]
	global_load_dword v51, v[70:71], off offset:32
	global_load_dword v72, v[70:71], off
	s_waitcnt vmcnt(1)
	v_mul_f32_e64 v69, |v51|, s3
	v_exp_f32_e32 v69, v69
	v_max_f32_e32 v51, v51, v51
	v_min_f32_e32 v51, 0, v51
	v_add_f32_e32 v73, 1.0, v69
	v_add_f32_e32 v74, -1.0, v73
	v_frexp_mant_f32_e32 v75, v73
	v_cvt_f64_f32_e32 v[70:71], v73
	v_sub_f32_e32 v76, v74, v73
	v_frexp_exp_i32_f64_e32 v70, v[70:71]
	v_cmp_gt_f32_e64 s[0:1], s24, v75
	v_sub_f32_e32 v74, v69, v74
	v_add_f32_e32 v71, 1.0, v76
	v_subbrev_co_u32_e64 v70, s[0:1], 0, v70, s[0:1]
	v_add_f32_e32 v71, v74, v71
	v_sub_u32_e32 v74, 0, v70
	v_cvt_f32_i32_e32 v70, v70
	v_ldexp_f32 v73, v73, v74
	v_ldexp_f32 v71, v71, v74
	v_add_f32_e32 v74, -1.0, v73
	v_add_f32_e32 v75, 1.0, v73
	v_add_f32_e32 v76, 1.0, v74
	v_add_f32_e32 v77, -1.0, v75
	v_sub_f32_e32 v76, v73, v76
	v_sub_f32_e32 v73, v73, v77
	v_mul_f32_e32 v77, 0x3f317218, v70
	v_add_f32_e32 v76, v71, v76
	v_add_f32_e32 v71, v71, v73
	v_fma_f32 v73, v70, s25, -v77
	v_add_f32_e32 v78, v74, v76
	v_add_f32_e32 v79, v75, v71
	v_fmac_f32_e32 v73, 0xb102e308, v70
	v_sub_f32_e32 v70, v78, v74
	v_sub_f32_e32 v74, v79, v75
	v_rcp_f32_e32 v75, v79
	v_add_f32_e32 v80, v77, v73
	v_sub_f32_e32 v71, v71, v74
	v_sub_f32_e32 v74, v80, v77
	v_sub_f32_e32 v73, v73, v74
	v_mul_f32_e32 v74, v78, v75
	v_sub_f32_e32 v70, v76, v70
	v_mul_f32_e32 v76, v79, v74
	v_fma_f32 v77, v74, v79, -v76
	v_fmac_f32_e32 v77, v74, v71
	v_add_f32_e32 v81, v76, v77
	v_sub_f32_e32 v82, v78, v81
	v_sub_f32_e32 v76, v81, v76
	v_sub_f32_e32 v78, v78, v82
	v_sub_f32_e32 v76, v76, v77
	v_sub_f32_e32 v77, v78, v81
	v_add_f32_e32 v70, v70, v77
	v_add_f32_e32 v70, v76, v70
	v_add_f32_e32 v76, v82, v70
	v_mul_f32_e32 v77, v75, v76
	v_sub_f32_e32 v78, v82, v76
	v_mul_f32_e32 v81, v79, v77
	v_add_f32_e32 v70, v70, v78
	v_add_f32_e32 v78, v74, v77
	v_fma_f32 v79, v77, v79, -v81
	v_sub_f32_e32 v74, v78, v74
	v_fmac_f32_e32 v79, v77, v71
	v_sub_f32_e32 v71, v77, v74
	v_add_f32_e32 v74, v81, v79
	v_sub_f32_e32 v77, v74, v81
	v_sub_f32_e32 v81, v76, v74
	v_sub_f32_e32 v76, v76, v81
	v_sub_f32_e32 v74, v76, v74
	v_sub_f32_e32 v77, v77, v79
	v_add_f32_e32 v70, v70, v74
	v_add_f32_e32 v70, v77, v70
	v_add_f32_e32 v70, v81, v70
	v_mul_f32_e32 v70, v75, v70
	v_add_f32_e32 v70, v71, v70
	v_add_f32_e32 v71, v78, v70
	v_mul_f32_e32 v74, v71, v71
	v_fmamk_f32 v77, v74, 0x3e9b6dac, v65
	v_sub_f32_e32 v75, v71, v78
	v_ldexp_f32 v76, v71, 1
	v_mul_f32_e32 v71, v71, v74
	v_fmaak_f32 v74, v74, v77, 0x3f2aaada
	v_mul_f32_e32 v71, v71, v74
	v_add_f32_e32 v74, v76, v71
	v_sub_f32_e32 v70, v70, v75
	v_sub_f32_e32 v75, v74, v76
	v_ldexp_f32 v70, v70, 1
	v_sub_f32_e32 v71, v71, v75
	v_add_f32_e32 v70, v70, v71
	v_add_f32_e32 v71, v74, v70
	v_sub_f32_e32 v74, v71, v74
	v_add_f32_e32 v75, v80, v71
	v_sub_f32_e32 v70, v70, v74
	v_sub_f32_e32 v74, v75, v80
	v_sub_f32_e32 v76, v75, v74
	v_sub_f32_e32 v71, v71, v74
	v_add_f32_e32 v74, v73, v70
	v_sub_f32_e32 v76, v80, v76
	v_sub_f32_e32 v77, v74, v73
	v_add_f32_e32 v71, v71, v76
	v_sub_f32_e32 v76, v74, v77
	v_sub_f32_e32 v70, v70, v77
	v_sub_f32_e32 v73, v73, v76
	v_add_f32_e32 v71, v74, v71
	v_add_f32_e32 v70, v70, v73
	v_add_f32_e32 v73, v75, v71
	v_sub_f32_e32 v74, v73, v75
	v_sub_f32_e32 v71, v71, v74
	v_add_f32_e32 v70, v70, v71
	v_add_f32_e32 v70, v73, v70
	v_cmp_neq_f32_e64 s[0:1], s26, v69
	s_nop 1
	v_cndmask_b32_e64 v70, v66, v70, s[0:1]
	v_cmp_ngt_f32_e64 s[0:1], -1.0, v69
	s_nop 1
	v_cndmask_b32_e64 v70, v67, v70, s[0:1]
	v_cmp_neq_f32_e64 s[0:1], -1.0, v69
	s_nop 1
	v_cndmask_b32_e64 v70, v68, v70, s[0:1]
	v_cmp_lt_f32_e64 s[0:1], |v69|, s27
	s_nop 1
	v_cndmask_b32_e64 v69, v70, v69, s[0:1]
	v_sub_f32_e32 v51, v51, v69
	v_mov_b32_e32 v69, v51
	s_nop 1
	v_add_f32_dpp v69, v69, v69 row_shr:1 row_mask:0xf bank_mask:0xf
	s_nop 1
	v_add_f32_dpp v69, v69, v69 row_shr:2 row_mask:0xf bank_mask:0xf
	s_nop 1
	v_add_f32_dpp v69, v69, v69 row_shr:4 row_mask:0xf bank_mask:0xf
	s_nop 1
	v_add_f32_dpp v69, v69, v69 row_shr:8 row_mask:0xf bank_mask:0xf
	s_nop 1
	v_add_f32_dpp v69, v69, v69 row_bcast:15 row_mask:0xa bank_mask:0xf
	s_nop 1
	v_add_f32_dpp v69, v69, v69 row_bcast:31 row_mask:0xc bank_mask:0xf
	s_waitcnt vmcnt(0)
	v_sub_f32_e32 v70, v72, v69
	v_add_u32_e32 v72, 0, v64
	v_add_u32_e32 v76, 0x12600, v72
	ds_write_b32 v76, v69
	v_add_u32_e32 v77, 0x14600, v72
	ds_write_b32 v77, v70
	v_add_u32_e32 v72, 0x16600, v72
	v_mov_b32_e32 v71, v70
	s_nop 1
	v_max_f32_dpp v71, v71, v71 row_shr:1 row_mask:0xf bank_mask:0xf
	s_nop 1
	v_max_f32_dpp v71, v71, v71 row_shr:2 row_mask:0xf bank_mask:0xf
	s_nop 1
	v_max_f32_dpp v71, v71, v71 row_shr:4 row_mask:0xf bank_mask:0xf
	s_nop 1
	v_max_f32_dpp v71, v71, v71 row_shr:8 row_mask:0xf bank_mask:0xf
	s_nop 1
	v_max_f32_dpp v71, v71, v71 row_bcast:15 row_mask:0xa bank_mask:0xf
	s_nop 1
	v_max_f32_dpp v71, v71, v71 row_bcast:31 row_mask:0xc bank_mask:0xf
	ds_write_b32 v72, v71
	s_nop 1
	v_readlane_b32 s100, v69, 63
	v_readlane_b32 s101, v71, 63
	s_and_saveexec_b64 s[0:1], s[10:11]
	s_cbranch_execz .LBB0_201
	v_add_u32_e32 v71, 0, v62
	v_add_u32_e32 v72, 0x18680, v71
	v_add_u32_e32 v71, 0x18600, v71
	v_mov_b32_e32 v51, s100
	v_add_f32_e32 v69, s101, v51
	ds_write_b32 v71, v51
	ds_write_b32 v72, v69
	s_branch .LBB0_201

; __device__ __forceinline__ void rwkv_sample_task(const Params& p, int s, int h) {
;     unsigned char* ws = p.ws;
;     const int lane = threadIdx.x & 63, rr = lane >> 4, cg_ = lane & 15;
;     const int row = MP + s;
;     const h16* ob = (const h16*)(ws + OFF_OPS16) + ((size_t)row * 8 + h) * 6 * 64;
;     f32x4 r4, d4, k4, a4, b4;
;     {
;         const h16x4 hr = *(const h16x4*)(ob + cg_ * 4), hw = *(const h16x4*)(ob + 64 + cg_ * 4), hk = *(const h16x4*)(ob + 128 + cg_ * 4),
;                     ha = *(const h16x4*)(ob + 256 + cg_ * 4), hb = *(const h16x4*)(ob + 320 + cg_ * 4);
; #pragma unroll
;         for (int j = 0; j < 4; ++j) { r4[j] = (float)hr[j]; d4[j] = __expf((float)hw[j]); k4[j] = (float)hk[j]; a4[j] = (float)ha[j]; b4[j] = (float)hb[j]; }
;     }
;     const float rk = ((const float*)(ws + OFF_RKS))[(size_t)row * 8 + h];
; __device__ __forceinline__ void p3_scan(const Params& p, LAS unsigned char* lds) {
;     ...
;     const int wave = threadIdx.x >> 6;
;     for (int i = blockIdx.x * 8 + wave; i < MS * 8; i += gridDim.x * 8) rwkv_sample_task(p, i >> 3, i & 7);
.LBB0_360:
	s_movk_i32 s0, 0x400
	v_and_b32_e32 v0, 7, v130
	v_lshrrev_b32_e32 v2, 3, v130
	v_xor_b32_e32 v3, v0, v2
	v_and_b32_e32 v3, 1, v3
	v_lshrrev_b32_e32 v2, 1, v2
	v_lshl_or_b32 v2, v2, 3, v0
	v_cmp_eq_u32_e32 vcc, 0, v3
	s_cmpk_eq_i32 s33, 0x100
	s_cselect_b64 s[98:99], -1, 0
	v_mov_b32_e32 v3, 0x7fff0000
	v_cndmask_b32_e32 v143, v3, v2, vcc
	v_cndmask_b32_e64 v143, v130, v143, s[98:99]
	v_cmp_gt_i32_e32 vcc, s0, v143
	s_and_saveexec_b64 s[38:39], vcc
	v_readlane_b32 s48, v253, 20
	v_readlane_b32 s49, v253, 21
	v_readlane_b32 s50, v253, 22
	v_readlane_b32 s51, v253, 23
	v_readlane_b32 s60, v253, 32
	v_readlane_b32 s61, v253, 33
	v_readlane_b32 s62, v253, 34
	v_readlane_b32 s63, v253, 35
	v_readlane_b32 s52, v253, 24
	v_readlane_b32 s53, v253, 25
	v_readlane_b32 s54, v253, 26
	v_readlane_b32 s55, v253, 27
	v_readlane_b32 s56, v253, 28
	v_readlane_b32 s57, v253, 29
	v_readlane_b32 s58, v253, 30
	v_readlane_b32 s59, v253, 31
	s_cbranch_execz .LBB0_363
	s_waitcnt vmcnt(5)
	v_mbcnt_hi_u32_b32 v1, -1, v225
	v_and_b32_e32 v3, 64, v1
	v_add_u32_e32 v3, 64, v3
	s_waitcnt vmcnt(4)
	v_xor_b32_e32 v5, 1, v1
	v_cmp_lt_i32_e64 s[0:1], v5, v3
	v_bfe_u32 v54, v132, 6, 3
	v_mov_b32_e32 v53, 0
	v_cndmask_b32_e64 v5, v1, v5, s[0:1]
	v_lshlrev_b32_e32 v55, 2, v5
	v_xor_b32_e32 v5, 2, v1
	v_cmp_lt_i32_e64 s[0:1], v5, v3
	v_lshlrev_b32_e32 v0, 6, v144
	v_or_b32_e32 v30, 60, v146
	v_cndmask_b32_e64 v5, v1, v5, s[0:1]
	v_lshlrev_b32_e32 v57, 2, v5
	v_xor_b32_e32 v5, 4, v1
	v_cmp_lt_i32_e64 s[0:1], v5, v3
	v_lshl_add_u64 v[34:35], s[62:63], 0, v[52:53]
	v_or_b32_e32 v2, 0x100, v0
	v_cndmask_b32_e64 v5, v1, v5, s[0:1]
	v_lshlrev_b32_e32 v129, 2, v5
	v_xor_b32_e32 v5, 8, v1
	v_cmp_lt_i32_e64 s[0:1], v5, v3
	v_or_b32_e32 v4, 0x200, v0
	v_or_b32_e32 v6, 0x300, v0
	v_cndmask_b32_e64 v5, v1, v5, s[0:1]
	v_lshlrev_b32_e32 v135, 2, v5
	v_xor_b32_e32 v5, 16, v1
	v_cmp_lt_i32_e64 s[0:1], v5, v3
	s_waitcnt vmcnt(3)
	v_or_b32_e32 v8, 0x400, v0
	v_or_b32_e32 v10, 0x500, v0
	v_cndmask_b32_e64 v5, v1, v5, s[0:1]
	v_lshlrev_b32_e32 v137, 2, v5
	v_xor_b32_e32 v5, 32, v1
	v_cmp_lt_i32_e64 s[0:1], v5, v3
	s_waitcnt vmcnt(2)
	v_or_b32_e32 v12, 0x600, v0
	v_or_b32_e32 v14, 0x700, v0
	v_cndmask_b32_e64 v1, v1, v5, s[0:1]
	v_lshlrev_b32_e32 v139, 2, v1
	v_lshlrev_b32_e32 v1, 6, v54
	s_mov_b64 s[0:1], s[76:77]
	v_readlane_b32 s64, v253, 4
	v_or3_b32 v1, v1, v36, v144
	v_readlane_b32 s76, v253, 16
	v_readlane_b32 s77, v253, 17
	s_waitcnt vmcnt(1)
	v_or_b32_e32 v16, 0x800, v0
	v_or_b32_e32 v18, 0x900, v0
	v_lshl_add_u64 v[58:59], s[76:77], 0, v[52:53]
	s_mov_b64 s[76:77], s[0:1]
	s_mov_b64 s[0:1], 0x546b100
	v_lshlrev_b32_e32 v52, 1, v1
	s_waitcnt vmcnt(0)
	v_or_b32_e32 v20, 0xa00, v0
	v_or_b32_e32 v22, 0xb00, v0
	v_or_b32_e32 v24, 0xc00, v0
	v_or_b32_e32 v26, 0xd00, v0
	v_or_b32_e32 v28, 0xe00, v0
	v_lshlrev_b32_e32 v32, 6, v30
	s_add_u32 s40, s82, 0x1aec800
	v_lshl_add_u64 v[60:61], v[34:35], 0, s[0:1]
	v_lshl_add_u64 v[62:63], s[62:63], 0, v[52:53]
	s_mov_b64 s[0:1], 0x2080000
	v_lshlrev_b32_e32 v52, 2, v1
	v_cmp_eq_u32_e32 vcc, 0, v131
	v_cmp_eq_u32_e64 s[4:5], 1, v131
	v_cmp_eq_u32_e64 s[6:7], 2, v131
	s_movk_i32 s3, 0x300
	v_cmp_eq_u32_e64 s[8:9], 3, v131
	v_cmp_eq_u32_e64 s[10:11], 4, v131
	v_cmp_eq_u32_e64 s[12:13], 5, v131
	v_cmp_eq_u32_e64 s[14:15], 6, v131
	v_cmp_eq_u32_e64 s[16:17], 7, v131
	v_cmp_eq_u32_e64 s[18:19], 8, v131
	v_cmp_eq_u32_e64 s[20:21], 9, v131
	v_cmp_eq_u32_e64 s[22:23], 10, v131
	v_cmp_eq_u32_e64 s[24:25], 11, v131
	v_cmp_eq_u32_e64 s[26:27], 12, v131
	v_cmp_eq_u32_e64 s[28:29], 13, v131
	v_cmp_eq_u32_e64 s[30:31], 14, v131
	v_cmp_eq_u32_e64 s[34:35], 15, v131
	v_lshlrev_b32_e32 v56, 12, v54
	s_addc_u32 s41, s83, 0
	v_lshl_add_u64 v[64:65], v[62:63], 0, s[0:1]
	v_lshl_add_u64 v[66:67], s[48:49], 0, v[52:53]
	v_lshl_add_u64 v[68:69], s[50:51], 0, v[52:53]
	s_mov_b64 s[42:43], 0
	v_lshlrev_b32_e32 v52, 1, v36
	v_lshlrev_b32_e32 v70, 1, v144
	v_lshlrev_b32_e32 v72, 2, v0
	v_lshlrev_b32_e32 v74, 2, v2
	v_lshlrev_b32_e32 v76, 2, v4
	v_lshlrev_b32_e32 v78, 2, v6
	v_lshlrev_b32_e32 v80, 2, v8
	v_lshlrev_b32_e32 v82, 2, v10
	v_lshlrev_b32_e32 v84, 2, v12
	v_lshlrev_b32_e32 v86, 2, v14
	v_lshlrev_b32_e32 v88, 2, v16
	v_lshlrev_b32_e32 v90, 2, v18
	v_lshlrev_b32_e32 v92, 2, v20
	v_lshlrev_b32_e32 v94, 2, v22
	v_lshlrev_b32_e32 v96, 2, v24
	v_lshlrev_b32_e32 v98, 2, v26
	v_lshlrev_b32_e32 v100, 2, v28
	v_lshlrev_b32_e32 v102, 1, v30
	v_lshlrev_b32_e32 v104, 2, v32
	v_mov_b32_e32 v141, 0x3a27c5ac
	s_mov_b32 s44, 0x800000
	s_movk_i32 s45, 0x3ff
	s_nop 0
	v_readlane_b32 s65, v253, 5
	v_readlane_b32 s66, v253, 6
	v_readlane_b32 s67, v253, 7
	v_readlane_b32 s68, v253, 8
	v_readlane_b32 s69, v253, 9
	v_readlane_b32 s70, v253, 10
	v_readlane_b32 s71, v253, 11
	v_readlane_b32 s72, v253, 12
	v_readlane_b32 s73, v253, 13
	v_readlane_b32 s74, v253, 14
	v_readlane_b32 s75, v253, 15
	v_readlane_b32 s78, v253, 18
	v_readlane_b32 s79, v253, 19

;     __device__ __forceinline__ void operator()(f32x4 (&acc)[2][2][4][2], const pg8::Unit& u, int wr, int wc, int fr, int fq) const {
;     ...
; #pragma unroll
;         for (int ai = 0; ai < 2; ++ai)
; #pragma unroll
;             for (int m = 0; m < 4; ++m) {
;                 const int row = row0 + ai * 128 + m * 16;
;                 const float rstd = rsqrtf(__hip_atomic_load(rowss + row, __ATOMIC_RELAXED, __HIP_MEMORY_SCOPE_AGENT) * (1.f / 1024.f) + EPS);
; #pragma unroll
;                 for (int bj = 0; bj < 2; ++bj) {
;                     const int c = col0 + bj * 128;
;                     const f32x4 w0 = *(const f32x4*)(nw + c), w1 = *(const f32x4*)(nw + c + 4);
;                     float* op = out + (size_t)row * D + c;
;                     *(f32x4*)op = acc[ai][bj][m][0] * rstd * w0; *(f32x4*)(op + 4) = acc[ai][bj][m][1] * rstd * w1;
;                 }
;             }
.LBB0_605:
	s_or_b64 exec, exec, s[4:5]
	s_barrier
	v_cmp_gt_u32_e64 s[98:99], 8, v131
	v_mov_b32_e32 v240, 0xffff8010
	v_cndmask_b32_e64 v236, v240, 0, s[98:99]
	v_cndmask_b32_e64 v237, -1, 0, s[98:99]
	v_mov_b32_e32 v240, 0x8010
	v_cndmask_b32_e64 v238, 0, v240, s[98:99]
	v_mov_b32_e32 v239, 0
	global_load_dword v147, v[112:113], off sc1
	v_lshlrev_b64 v[166:167], 2, v[140:141]
	v_lshl_add_u64 v[140:141], s[60:61], 0, v[166:167]
	global_load_dwordx4 v[168:171], v[140:141], off
	global_load_dwordx4 v[172:175], v[140:141], off offset:16
	v_mov_b32_e32 v137, 0x358637bd
	s_mov_b32 s0, 0x800000
	v_lshlrev_b64 v[138:139], 12, v[138:139]
	v_lshl_add_u64 v[138:139], s[62:63], 0, v[138:139]
	v_lshl_add_u64 v[138:139], v[138:139], 0, v[166:167]
	v_lshlrev_b64 v[104:105], 12, v[104:105]
	v_lshl_add_u64 v[104:105], s[62:63], 0, v[104:105]
	v_lshl_add_u64 v[104:105], v[104:105], 0, v[166:167]
	v_lshlrev_b64 v[88:89], 12, v[88:89]
	v_lshl_add_u64 v[88:89], s[62:63], 0, v[88:89]
	v_lshl_add_u64 v[88:89], v[88:89], 0, v[166:167]
	v_lshlrev_b64 v[72:73], 12, v[72:73]
	v_lshl_add_u64 v[72:73], s[62:63], 0, v[72:73]
	v_lshl_add_u64 v[72:73], v[72:73], 0, v[166:167]
	v_lshlrev_b64 v[56:57], 12, v[56:57]
	v_lshl_add_u64 v[56:57], s[62:63], 0, v[56:57]
	v_lshl_add_u64 v[56:57], v[56:57], 0, v[166:167]
	v_lshlrev_b64 v[40:41], 12, v[40:41]
	v_lshl_add_u64 v[40:41], s[62:63], 0, v[40:41]
	v_lshl_add_u64 v[40:41], v[40:41], 0, v[166:167]
	v_lshlrev_b64 v[24:25], 12, v[24:25]
	v_lshl_add_u64 v[24:25], s[62:63], 0, v[24:25]
	v_lshl_add_u64 v[24:25], v[24:25], 0, v[166:167]
	s_waitcnt vmcnt(2)
	v_fmamk_f32 v147, v147, 0x3a800000, v137
	v_mul_f32_e32 v176, 0x4b800000, v147
	v_cmp_gt_f32_e32 vcc, s0, v147
	s_nop 1
	v_cndmask_b32_e32 v147, v147, v176, vcc
	v_rsq_f32_e32 v147, v147
	s_nop 0
	v_mul_f32_e32 v176, 0x45800000, v147
	v_cndmask_b32_e32 v176, v147, v176, vcc
	v_pk_mul_f32 v[142:143], v[142:143], v[176:177] op_sel_hi:[1,0]
	v_pk_mul_f32 v[126:127], v[126:127], v[176:177] op_sel_hi:[1,0]
	v_pk_mul_f32 v[178:179], v[124:125], v[176:177] op_sel_hi:[1,0]
	v_pk_mul_f32 v[180:181], v[122:123], v[176:177] op_sel_hi:[1,0]
	s_waitcnt vmcnt(1)
	v_pk_mul_f32 v[124:125], v[170:171], v[126:127]
	v_pk_mul_f32 v[122:123], v[168:169], v[142:143]
	s_waitcnt vmcnt(0)
	v_pk_mul_f32 v[170:171], v[174:175], v[180:181]
	v_pk_mul_f32 v[168:169], v[172:173], v[178:179]
	s_nop 1
	v_mov_b32_dpp v228, v168 row_ror:8 row_mask:0xf bank_mask:0xf
	v_mov_b32_dpp v229, v169 row_ror:8 row_mask:0xf bank_mask:0xf
	v_mov_b32_dpp v230, v170 row_ror:8 row_mask:0xf bank_mask:0xf
	v_mov_b32_dpp v231, v171 row_ror:8 row_mask:0xf bank_mask:0xf
	v_cndmask_b32_e64 v168, v228, v122, s[98:99]
	v_cndmask_b32_e64 v169, v229, v123, s[98:99]
	v_cndmask_b32_e64 v170, v230, v124, s[98:99]
	v_cndmask_b32_e64 v171, v231, v125, s[98:99]
	v_cndmask_b32_e64 v228, v122, v228, s[98:99]
	v_cndmask_b32_e64 v229, v123, v229, s[98:99]
	v_cndmask_b32_e64 v230, v124, v230, s[98:99]
	v_cndmask_b32_e64 v231, v125, v231, s[98:99]
	v_lshl_add_u64 v[232:233], v[138:139], 0, v[236:237]
	v_lshl_add_u64 v[234:235], v[138:139], 0, v[238:239]
	global_store_dwordx4 v[232:233], v[168:171], off
	global_store_dwordx4 v[234:235], v[228:231], off
	global_load_dwordx4 v[122:125], v[140:141], off offset:512
	s_nop 0
	global_load_dwordx4 v[168:171], v[140:141], off offset:528
	v_pk_mul_f32 v[118:119], v[118:119], v[176:177] op_sel_hi:[1,0]
	v_pk_mul_f32 v[120:121], v[120:121], v[176:177] op_sel_hi:[1,0]
	v_pk_mul_f32 v[126:127], v[114:115], v[176:177] op_sel_hi:[1,0]
	v_pk_mul_f32 v[142:143], v[116:117], v[176:177] op_sel_hi:[1,0]
	s_waitcnt vmcnt(1)
	v_pk_mul_f32 v[114:115], v[122:123], v[120:121]
	v_pk_mul_f32 v[116:117], v[124:125], v[118:119]
	s_waitcnt vmcnt(0)
	v_pk_mul_f32 v[118:119], v[168:169], v[142:143]
	v_pk_mul_f32 v[120:121], v[170:171], v[126:127]
	s_nop 1
	v_mov_b32_dpp v228, v118 row_ror:8 row_mask:0xf bank_mask:0xf
	v_mov_b32_dpp v229, v119 row_ror:8 row_mask:0xf bank_mask:0xf
	v_mov_b32_dpp v230, v120 row_ror:8 row_mask:0xf bank_mask:0xf
	v_mov_b32_dpp v231, v121 row_ror:8 row_mask:0xf bank_mask:0xf
	v_cndmask_b32_e64 v118, v228, v114, s[98:99]
	v_cndmask_b32_e64 v119, v229, v115, s[98:99]
	v_cndmask_b32_e64 v120, v230, v116, s[98:99]
	v_cndmask_b32_e64 v121, v231, v117, s[98:99]
	v_cndmask_b32_e64 v228, v114, v228, s[98:99]
	v_cndmask_b32_e64 v229, v115, v229, s[98:99]
	v_cndmask_b32_e64 v230, v116, v230, s[98:99]
	v_cndmask_b32_e64 v231, v117, v231, s[98:99]
	v_lshl_add_u64 v[232:233], v[138:139], 0, v[236:237]
	v_lshl_add_u64 v[234:235], v[138:139], 0, v[238:239]
	global_store_dwordx4 v[232:233], v[118:121], off offset:512
	global_store_dwordx4 v[234:235], v[228:231], off offset:512
	global_load_dword v122, v[152:153], off sc1
	s_nop 0
	global_load_dwordx4 v[114:117], v[140:141], off
	global_load_dwordx4 v[118:121], v[140:141], off offset:16
	s_waitcnt vmcnt(2)
	v_fmamk_f32 v122, v122, 0x3a800000, v137
	v_mul_f32_e32 v123, 0x4b800000, v122
	v_cmp_gt_f32_e32 vcc, s0, v122
	s_nop 1
	v_cndmask_b32_e32 v122, v122, v123, vcc
	v_rsq_f32_e32 v124, v122
	v_lshlrev_b64 v[122:123], 12, v[144:145]
	v_lshl_add_u64 v[122:123], s[62:63], 0, v[122:123]
	v_lshl_add_u64 v[122:123], v[122:123], 0, v[166:167]
	v_mul_f32_e32 v125, 0x45800000, v124
	v_cndmask_b32_e32 v124, v124, v125, vcc
	v_pk_mul_f32 v[126:127], v[148:149], v[124:125] op_sel_hi:[1,0]
	v_pk_mul_f32 v[110:111], v[110:111], v[124:125] op_sel_hi:[1,0]
	v_pk_mul_f32 v[138:139], v[108:109], v[124:125] op_sel_hi:[1,0]
	v_pk_mul_f32 v[142:143], v[106:107], v[124:125] op_sel_hi:[1,0]
	s_waitcnt vmcnt(1)
	v_pk_mul_f32 v[108:109], v[116:117], v[110:111]
	v_pk_mul_f32 v[106:107], v[114:115], v[126:127]
	s_waitcnt vmcnt(0)
;     __device__ __forceinline__ void operator()(f32x4 (&acc)[2][2][4][2], const pg8::Unit& u, int wr, int wc, int fr, int fq) const {
;     ...
; #pragma unroll
;         for (int ai = 0; ai < 2; ++ai)
; #pragma unroll
;             for (int m = 0; m < 4; ++m) {
;                 const int row = row0 + ai * 128 + m * 16;
;                 const float rstd = rsqrtf(__hip_atomic_load(rowss + row, __ATOMIC_RELAXED, __HIP_MEMORY_SCOPE_AGENT) * (1.f / 1024.f) + EPS);
; #pragma unroll
;                 for (int bj = 0; bj < 2; ++bj) {
;                     const int c = col0 + bj * 128;
;                     const f32x4 w0 = *(const f32x4*)(nw + c), w1 = *(const f32x4*)(nw + c + 4);
;                     float* op = out + (size_t)row * D + c;
;                     *(f32x4*)op = acc[ai][bj][m][0] * rstd * w0; *(f32x4*)(op + 4) = acc[ai][bj][m][1] * rstd * w1;
;                 }
;             }
	v_pk_mul_f32 v[116:117], v[120:121], v[142:143]
	v_pk_mul_f32 v[114:115], v[118:119], v[138:139]
	s_nop 1
	v_mov_b32_dpp v228, v114 row_ror:8 row_mask:0xf bank_mask:0xf
	v_mov_b32_dpp v229, v115 row_ror:8 row_mask:0xf bank_mask:0xf
	v_mov_b32_dpp v230, v116 row_ror:8 row_mask:0xf bank_mask:0xf
	v_mov_b32_dpp v231, v117 row_ror:8 row_mask:0xf bank_mask:0xf
	v_cndmask_b32_e64 v114, v228, v106, s[98:99]
	v_cndmask_b32_e64 v115, v229, v107, s[98:99]
	v_cndmask_b32_e64 v116, v230, v108, s[98:99]
	v_cndmask_b32_e64 v117, v231, v109, s[98:99]
	v_cndmask_b32_e64 v228, v106, v228, s[98:99]
	v_cndmask_b32_e64 v229, v107, v229, s[98:99]
	v_cndmask_b32_e64 v230, v108, v230, s[98:99]
	v_cndmask_b32_e64 v231, v109, v231, s[98:99]
	v_lshl_add_u64 v[232:233], v[122:123], 0, v[236:237]
	v_lshl_add_u64 v[234:235], v[122:123], 0, v[238:239]
	global_store_dwordx4 v[232:233], v[114:117], off
	global_store_dwordx4 v[234:235], v[228:231], off
	global_load_dwordx4 v[106:109], v[140:141], off offset:512
	s_nop 0
	global_load_dwordx4 v[114:117], v[140:141], off offset:528
	v_pk_mul_f32 v[102:103], v[102:103], v[124:125] op_sel_hi:[1,0]
	v_pk_mul_f32 v[100:101], v[100:101], v[124:125] op_sel_hi:[1,0]
	v_pk_mul_f32 v[110:111], v[98:99], v[124:125] op_sel_hi:[1,0]
	v_pk_mul_f32 v[118:119], v[96:97], v[124:125] op_sel_hi:[1,0]
	s_waitcnt vmcnt(1)
	v_pk_mul_f32 v[96:97], v[106:107], v[100:101]
	v_pk_mul_f32 v[98:99], v[108:109], v[102:103]
	s_waitcnt vmcnt(0)
	v_pk_mul_f32 v[100:101], v[114:115], v[118:119]
	v_pk_mul_f32 v[102:103], v[116:117], v[110:111]
	s_nop 1
	v_mov_b32_dpp v228, v100 row_ror:8 row_mask:0xf bank_mask:0xf
	v_mov_b32_dpp v229, v101 row_ror:8 row_mask:0xf bank_mask:0xf
	v_mov_b32_dpp v230, v102 row_ror:8 row_mask:0xf bank_mask:0xf
	v_mov_b32_dpp v231, v103 row_ror:8 row_mask:0xf bank_mask:0xf
	v_cndmask_b32_e64 v100, v228, v96, s[98:99]
	v_cndmask_b32_e64 v101, v229, v97, s[98:99]
	v_cndmask_b32_e64 v102, v230, v98, s[98:99]
	v_cndmask_b32_e64 v103, v231, v99, s[98:99]
	v_cndmask_b32_e64 v228, v96, v228, s[98:99]
	v_cndmask_b32_e64 v229, v97, v229, s[98:99]
	v_cndmask_b32_e64 v230, v98, v230, s[98:99]
	v_cndmask_b32_e64 v231, v99, v231, s[98:99]
	v_lshl_add_u64 v[232:233], v[122:123], 0, v[236:237]
	v_lshl_add_u64 v[234:235], v[122:123], 0, v[238:239]
	global_store_dwordx4 v[232:233], v[100:103], off offset:512
	global_store_dwordx4 v[234:235], v[228:231], off offset:512
	global_load_dword v106, v[156:157], off sc1
	s_nop 0
	global_load_dwordx4 v[96:99], v[140:141], off
	global_load_dwordx4 v[100:103], v[140:141], off offset:16
	s_waitcnt vmcnt(2)
	v_fmamk_f32 v106, v106, 0x3a800000, v137
	v_mul_f32_e32 v107, 0x4b800000, v106
	v_cmp_gt_f32_e32 vcc, s0, v106
	s_nop 1
	v_cndmask_b32_e32 v106, v106, v107, vcc
	v_rsq_f32_e32 v106, v106
	s_nop 0
	v_mul_f32_e32 v107, 0x45800000, v106
	v_cndmask_b32_e32 v106, v106, v107, vcc
	v_pk_mul_f32 v[108:109], v[150:151], v[106:107] op_sel_hi:[1,0]
	v_pk_mul_f32 v[94:95], v[94:95], v[106:107] op_sel_hi:[1,0]
	v_pk_mul_f32 v[110:111], v[92:93], v[106:107] op_sel_hi:[1,0]
	v_pk_mul_f32 v[114:115], v[90:91], v[106:107] op_sel_hi:[1,0]
	s_waitcnt vmcnt(1)
	v_pk_mul_f32 v[92:93], v[98:99], v[94:95]
	v_pk_mul_f32 v[90:91], v[96:97], v[108:109]
	s_waitcnt vmcnt(0)
	v_pk_mul_f32 v[96:97], v[102:103], v[114:115]
	v_pk_mul_f32 v[94:95], v[100:101], v[110:111]
	s_nop 1
	v_mov_b32_dpp v228, v94 row_ror:8 row_mask:0xf bank_mask:0xf
	v_mov_b32_dpp v229, v95 row_ror:8 row_mask:0xf bank_mask:0xf
	v_mov_b32_dpp v230, v96 row_ror:8 row_mask:0xf bank_mask:0xf
	v_mov_b32_dpp v231, v97 row_ror:8 row_mask:0xf bank_mask:0xf
	v_cndmask_b32_e64 v94, v228, v90, s[98:99]
	v_cndmask_b32_e64 v95, v229, v91, s[98:99]
	v_cndmask_b32_e64 v96, v230, v92, s[98:99]
	v_cndmask_b32_e64 v97, v231, v93, s[98:99]
	v_cndmask_b32_e64 v228, v90, v228, s[98:99]
	v_cndmask_b32_e64 v229, v91, v229, s[98:99]
	v_cndmask_b32_e64 v230, v92, v230, s[98:99]
	v_cndmask_b32_e64 v231, v93, v231, s[98:99]
	v_lshl_add_u64 v[232:233], v[104:105], 0, v[236:237]
	v_lshl_add_u64 v[234:235], v[104:105], 0, v[238:239]
	global_store_dwordx4 v[232:233], v[94:97], off
	global_store_dwordx4 v[234:235], v[228:231], off
	global_load_dwordx4 v[90:93], v[140:141], off offset:512
	s_nop 0
	global_load_dwordx4 v[94:97], v[140:141], off offset:528
	v_pk_mul_f32 v[86:87], v[86:87], v[106:107] op_sel_hi:[1,0]
	v_pk_mul_f32 v[84:85], v[84:85], v[106:107] op_sel_hi:[1,0]
	v_pk_mul_f32 v[98:99], v[82:83], v[106:107] op_sel_hi:[1,0]
	v_pk_mul_f32 v[100:101], v[80:81], v[106:107] op_sel_hi:[1,0]
	s_waitcnt vmcnt(1)
	v_pk_mul_f32 v[80:81], v[90:91], v[84:85]
	v_pk_mul_f32 v[82:83], v[92:93], v[86:87]
	s_waitcnt vmcnt(0)
	v_pk_mul_f32 v[84:85], v[94:95], v[100:101]
	v_pk_mul_f32 v[86:87], v[96:97], v[98:99]
	s_nop 1
	v_mov_b32_dpp v228, v84 row_ror:8 row_mask:0xf bank_mask:0xf
	v_mov_b32_dpp v229, v85 row_ror:8 row_mask:0xf bank_mask:0xf
	v_mov_b32_dpp v230, v86 row_ror:8 row_mask:0xf bank_mask:0xf
	v_mov_b32_dpp v231, v87 row_ror:8 row_mask:0xf bank_mask:0xf
	v_cndmask_b32_e64 v84, v228, v80, s[98:99]
	v_cndmask_b32_e64 v85, v229, v81, s[98:99]
	v_cndmask_b32_e64 v86, v230, v82, s[98:99]
	v_cndmask_b32_e64 v87, v231, v83, s[98:99]
	v_cndmask_b32_e64 v228, v80, v228, s[98:99]
	v_cndmask_b32_e64 v229, v81, v229, s[98:99]
	v_cndmask_b32_e64 v230, v82, v230, s[98:99]
	v_cndmask_b32_e64 v231, v83, v231, s[98:99]
	v_lshl_add_u64 v[232:233], v[104:105], 0, v[236:237]
	v_lshl_add_u64 v[234:235], v[104:105], 0, v[238:239]
	global_store_dwordx4 v[232:233], v[84:87], off offset:512
	global_store_dwordx4 v[234:235], v[228:231], off offset:512
	global_load_dword v90, v[160:161], off sc1
	s_nop 0
	global_load_dwordx4 v[80:83], v[140:141], off
	global_load_dwordx4 v[84:87], v[140:141], off offset:16
	s_waitcnt vmcnt(2)
;     __device__ __forceinline__ void operator()(f32x4 (&acc)[2][2][4][2], const pg8::Unit& u, int wr, int wc, int fr, int fq) const {
;     ...
; #pragma unroll
;         for (int ai = 0; ai < 2; ++ai)
; #pragma unroll
;             for (int m = 0; m < 4; ++m) {
;                 const int row = row0 + ai * 128 + m * 16;
;                 const float rstd = rsqrtf(__hip_atomic_load(rowss + row, __ATOMIC_RELAXED, __HIP_MEMORY_SCOPE_AGENT) * (1.f / 1024.f) + EPS);
; #pragma unroll
;                 for (int bj = 0; bj < 2; ++bj) {
;                     const int c = col0 + bj * 128;
;                     const f32x4 w0 = *(const f32x4*)(nw + c), w1 = *(const f32x4*)(nw + c + 4);
;                     float* op = out + (size_t)row * D + c;
;                     *(f32x4*)op = acc[ai][bj][m][0] * rstd * w0; *(f32x4*)(op + 4) = acc[ai][bj][m][1] * rstd * w1;
;                 }
;             }
	v_fmamk_f32 v90, v90, 0x3a800000, v137
	v_mul_f32_e32 v91, 0x4b800000, v90
	v_cmp_gt_f32_e32 vcc, s0, v90
	s_nop 1
	v_cndmask_b32_e32 v90, v90, v91, vcc
	v_rsq_f32_e32 v90, v90
	s_nop 0
	v_mul_f32_e32 v91, 0x45800000, v90
	v_cndmask_b32_e32 v90, v90, v91, vcc
	v_pk_mul_f32 v[92:93], v[154:155], v[90:91] op_sel_hi:[1,0]
	v_pk_mul_f32 v[78:79], v[78:79], v[90:91] op_sel_hi:[1,0]
	v_pk_mul_f32 v[94:95], v[76:77], v[90:91] op_sel_hi:[1,0]
	v_pk_mul_f32 v[96:97], v[74:75], v[90:91] op_sel_hi:[1,0]
	s_waitcnt vmcnt(1)
	v_pk_mul_f32 v[76:77], v[82:83], v[78:79]
	v_pk_mul_f32 v[74:75], v[80:81], v[92:93]
	s_waitcnt vmcnt(0)
	v_pk_mul_f32 v[80:81], v[86:87], v[96:97]
	v_pk_mul_f32 v[78:79], v[84:85], v[94:95]
	s_nop 1
	v_mov_b32_dpp v228, v78 row_ror:8 row_mask:0xf bank_mask:0xf
	v_mov_b32_dpp v229, v79 row_ror:8 row_mask:0xf bank_mask:0xf
	v_mov_b32_dpp v230, v80 row_ror:8 row_mask:0xf bank_mask:0xf
	v_mov_b32_dpp v231, v81 row_ror:8 row_mask:0xf bank_mask:0xf
	v_cndmask_b32_e64 v78, v228, v74, s[98:99]
	v_cndmask_b32_e64 v79, v229, v75, s[98:99]
	v_cndmask_b32_e64 v80, v230, v76, s[98:99]
	v_cndmask_b32_e64 v81, v231, v77, s[98:99]
	v_cndmask_b32_e64 v228, v74, v228, s[98:99]
	v_cndmask_b32_e64 v229, v75, v229, s[98:99]
	v_cndmask_b32_e64 v230, v76, v230, s[98:99]
	v_cndmask_b32_e64 v231, v77, v231, s[98:99]
	v_lshl_add_u64 v[232:233], v[88:89], 0, v[236:237]
	v_lshl_add_u64 v[234:235], v[88:89], 0, v[238:239]
	global_store_dwordx4 v[232:233], v[78:81], off
	global_store_dwordx4 v[234:235], v[228:231], off
	global_load_dwordx4 v[74:77], v[140:141], off offset:512
	s_nop 0
	global_load_dwordx4 v[78:81], v[140:141], off offset:528
	v_pk_mul_f32 v[70:71], v[70:71], v[90:91] op_sel_hi:[1,0]
	v_pk_mul_f32 v[68:69], v[68:69], v[90:91] op_sel_hi:[1,0]
	v_pk_mul_f32 v[82:83], v[66:67], v[90:91] op_sel_hi:[1,0]
	v_pk_mul_f32 v[84:85], v[64:65], v[90:91] op_sel_hi:[1,0]
	s_waitcnt vmcnt(1)
	v_pk_mul_f32 v[64:65], v[74:75], v[68:69]
	v_pk_mul_f32 v[66:67], v[76:77], v[70:71]
	s_waitcnt vmcnt(0)
	v_pk_mul_f32 v[68:69], v[78:79], v[84:85]
	v_pk_mul_f32 v[70:71], v[80:81], v[82:83]
	s_nop 1
	v_mov_b32_dpp v228, v68 row_ror:8 row_mask:0xf bank_mask:0xf
	v_mov_b32_dpp v229, v69 row_ror:8 row_mask:0xf bank_mask:0xf
	v_mov_b32_dpp v230, v70 row_ror:8 row_mask:0xf bank_mask:0xf
	v_mov_b32_dpp v231, v71 row_ror:8 row_mask:0xf bank_mask:0xf
	v_cndmask_b32_e64 v68, v228, v64, s[98:99]
	v_cndmask_b32_e64 v69, v229, v65, s[98:99]
	v_cndmask_b32_e64 v70, v230, v66, s[98:99]
	v_cndmask_b32_e64 v71, v231, v67, s[98:99]
	v_cndmask_b32_e64 v228, v64, v228, s[98:99]
	v_cndmask_b32_e64 v229, v65, v229, s[98:99]
	v_cndmask_b32_e64 v230, v66, v230, s[98:99]
	v_cndmask_b32_e64 v231, v67, v231, s[98:99]
	v_lshl_add_u64 v[232:233], v[88:89], 0, v[236:237]
	v_lshl_add_u64 v[234:235], v[88:89], 0, v[238:239]
	global_store_dwordx4 v[232:233], v[68:71], off offset:512
	global_store_dwordx4 v[234:235], v[228:231], off offset:512
	global_load_dword v74, v[112:113], off offset:512 sc1
	s_nop 0
	global_load_dwordx4 v[64:67], v[140:141], off
	global_load_dwordx4 v[68:71], v[140:141], off offset:16
	s_waitcnt vmcnt(2)
	v_fmamk_f32 v74, v74, 0x3a800000, v137
	v_mul_f32_e32 v75, 0x4b800000, v74
	v_cmp_gt_f32_e32 vcc, s0, v74
	s_nop 1
	v_cndmask_b32_e32 v74, v74, v75, vcc
	v_rsq_f32_e32 v74, v74
	s_nop 0
	v_mul_f32_e32 v75, 0x45800000, v74
	v_cndmask_b32_e32 v74, v74, v75, vcc
	v_pk_mul_f32 v[76:77], v[158:159], v[74:75] op_sel_hi:[1,0]
	v_pk_mul_f32 v[62:63], v[62:63], v[74:75] op_sel_hi:[1,0]
	v_pk_mul_f32 v[78:79], v[60:61], v[74:75] op_sel_hi:[1,0]
	v_pk_mul_f32 v[80:81], v[58:59], v[74:75] op_sel_hi:[1,0]
	s_waitcnt vmcnt(1)
	v_pk_mul_f32 v[60:61], v[66:67], v[62:63]
	v_pk_mul_f32 v[58:59], v[64:65], v[76:77]
	s_waitcnt vmcnt(0)
	v_pk_mul_f32 v[64:65], v[70:71], v[80:81]
	v_pk_mul_f32 v[62:63], v[68:69], v[78:79]
	s_nop 1
	v_mov_b32_dpp v228, v62 row_ror:8 row_mask:0xf bank_mask:0xf
	v_mov_b32_dpp v229, v63 row_ror:8 row_mask:0xf bank_mask:0xf
	v_mov_b32_dpp v230, v64 row_ror:8 row_mask:0xf bank_mask:0xf
	v_mov_b32_dpp v231, v65 row_ror:8 row_mask:0xf bank_mask:0xf
	v_cndmask_b32_e64 v62, v228, v58, s[98:99]
	v_cndmask_b32_e64 v63, v229, v59, s[98:99]
	v_cndmask_b32_e64 v64, v230, v60, s[98:99]
	v_cndmask_b32_e64 v65, v231, v61, s[98:99]
	v_cndmask_b32_e64 v228, v58, v228, s[98:99]
	v_cndmask_b32_e64 v229, v59, v229, s[98:99]
	v_cndmask_b32_e64 v230, v60, v230, s[98:99]
	v_cndmask_b32_e64 v231, v61, v231, s[98:99]
	v_lshl_add_u64 v[232:233], v[72:73], 0, v[236:237]
	v_lshl_add_u64 v[234:235], v[72:73], 0, v[238:239]
	global_store_dwordx4 v[232:233], v[62:65], off
	global_store_dwordx4 v[234:235], v[228:231], off
	global_load_dwordx4 v[58:61], v[140:141], off offset:512
	s_nop 0
	global_load_dwordx4 v[62:65], v[140:141], off offset:528
	v_pk_mul_f32 v[54:55], v[54:55], v[74:75] op_sel_hi:[1,0]
	v_pk_mul_f32 v[52:53], v[52:53], v[74:75] op_sel_hi:[1,0]
	v_pk_mul_f32 v[66:67], v[50:51], v[74:75] op_sel_hi:[1,0]
	v_pk_mul_f32 v[68:69], v[48:49], v[74:75] op_sel_hi:[1,0]
	s_waitcnt vmcnt(1)
	v_pk_mul_f32 v[48:49], v[58:59], v[52:53]
	v_pk_mul_f32 v[50:51], v[60:61], v[54:55]
	s_waitcnt vmcnt(0)
;     __device__ __forceinline__ void operator()(f32x4 (&acc)[2][2][4][2], const pg8::Unit& u, int wr, int wc, int fr, int fq) const {
;     ...
; #pragma unroll
;         for (int ai = 0; ai < 2; ++ai)
; #pragma unroll
;             for (int m = 0; m < 4; ++m) {
;                 const int row = row0 + ai * 128 + m * 16;
;                 const float rstd = rsqrtf(__hip_atomic_load(rowss + row, __ATOMIC_RELAXED, __HIP_MEMORY_SCOPE_AGENT) * (1.f / 1024.f) + EPS);
; #pragma unroll
;                 for (int bj = 0; bj < 2; ++bj) {
;                     const int c = col0 + bj * 128;
;                     const f32x4 w0 = *(const f32x4*)(nw + c), w1 = *(const f32x4*)(nw + c + 4);
;                     float* op = out + (size_t)row * D + c;
;                     *(f32x4*)op = acc[ai][bj][m][0] * rstd * w0; *(f32x4*)(op + 4) = acc[ai][bj][m][1] * rstd * w1;
;                 }
;             }
	v_pk_mul_f32 v[52:53], v[62:63], v[68:69]
	v_pk_mul_f32 v[54:55], v[64:65], v[66:67]
	s_nop 1
	v_mov_b32_dpp v228, v52 row_ror:8 row_mask:0xf bank_mask:0xf
	v_mov_b32_dpp v229, v53 row_ror:8 row_mask:0xf bank_mask:0xf
	v_mov_b32_dpp v230, v54 row_ror:8 row_mask:0xf bank_mask:0xf
	v_mov_b32_dpp v231, v55 row_ror:8 row_mask:0xf bank_mask:0xf
	v_cndmask_b32_e64 v52, v228, v48, s[98:99]
	v_cndmask_b32_e64 v53, v229, v49, s[98:99]
	v_cndmask_b32_e64 v54, v230, v50, s[98:99]
	v_cndmask_b32_e64 v55, v231, v51, s[98:99]
	v_cndmask_b32_e64 v228, v48, v228, s[98:99]
	v_cndmask_b32_e64 v229, v49, v229, s[98:99]
	v_cndmask_b32_e64 v230, v50, v230, s[98:99]
	v_cndmask_b32_e64 v231, v51, v231, s[98:99]
	v_lshl_add_u64 v[232:233], v[72:73], 0, v[236:237]
	v_lshl_add_u64 v[234:235], v[72:73], 0, v[238:239]
	global_store_dwordx4 v[232:233], v[52:55], off offset:512
	global_store_dwordx4 v[234:235], v[228:231], off offset:512
	global_load_dword v58, v[112:113], off offset:576 sc1
	s_nop 0
	global_load_dwordx4 v[48:51], v[140:141], off
	global_load_dwordx4 v[52:55], v[140:141], off offset:16
	s_waitcnt vmcnt(2)
	v_fmamk_f32 v58, v58, 0x3a800000, v137
	v_mul_f32_e32 v59, 0x4b800000, v58
	v_cmp_gt_f32_e32 vcc, s0, v58
	s_nop 1
	v_cndmask_b32_e32 v58, v58, v59, vcc
	v_rsq_f32_e32 v58, v58
	s_nop 0
	v_mul_f32_e32 v59, 0x45800000, v58
	v_cndmask_b32_e32 v58, v58, v59, vcc
	v_pk_mul_f32 v[60:61], v[162:163], v[58:59] op_sel_hi:[1,0]
	v_pk_mul_f32 v[46:47], v[46:47], v[58:59] op_sel_hi:[1,0]
	v_pk_mul_f32 v[62:63], v[44:45], v[58:59] op_sel_hi:[1,0]
	v_pk_mul_f32 v[64:65], v[42:43], v[58:59] op_sel_hi:[1,0]
	s_waitcnt vmcnt(1)
	v_pk_mul_f32 v[44:45], v[50:51], v[46:47]
	v_pk_mul_f32 v[42:43], v[48:49], v[60:61]
	s_waitcnt vmcnt(0)
	v_pk_mul_f32 v[48:49], v[54:55], v[64:65]
	v_pk_mul_f32 v[46:47], v[52:53], v[62:63]
	s_nop 1
	v_mov_b32_dpp v228, v46 row_ror:8 row_mask:0xf bank_mask:0xf
	v_mov_b32_dpp v229, v47 row_ror:8 row_mask:0xf bank_mask:0xf
	v_mov_b32_dpp v230, v48 row_ror:8 row_mask:0xf bank_mask:0xf
	v_mov_b32_dpp v231, v49 row_ror:8 row_mask:0xf bank_mask:0xf
	v_cndmask_b32_e64 v46, v228, v42, s[98:99]
	v_cndmask_b32_e64 v47, v229, v43, s[98:99]
	v_cndmask_b32_e64 v48, v230, v44, s[98:99]
	v_cndmask_b32_e64 v49, v231, v45, s[98:99]
	v_cndmask_b32_e64 v228, v42, v228, s[98:99]
	v_cndmask_b32_e64 v229, v43, v229, s[98:99]
	v_cndmask_b32_e64 v230, v44, v230, s[98:99]
	v_cndmask_b32_e64 v231, v45, v231, s[98:99]
	v_lshl_add_u64 v[232:233], v[56:57], 0, v[236:237]
	v_lshl_add_u64 v[234:235], v[56:57], 0, v[238:239]
	global_store_dwordx4 v[232:233], v[46:49], off
	global_store_dwordx4 v[234:235], v[228:231], off
	global_load_dwordx4 v[42:45], v[140:141], off offset:512
	s_nop 0
	global_load_dwordx4 v[46:49], v[140:141], off offset:528
	v_pk_mul_f32 v[38:39], v[38:39], v[58:59] op_sel_hi:[1,0]
	v_pk_mul_f32 v[36:37], v[36:37], v[58:59] op_sel_hi:[1,0]
	v_pk_mul_f32 v[50:51], v[34:35], v[58:59] op_sel_hi:[1,0]
	v_pk_mul_f32 v[52:53], v[32:33], v[58:59] op_sel_hi:[1,0]
	s_waitcnt vmcnt(1)
	v_pk_mul_f32 v[32:33], v[42:43], v[36:37]
	v_pk_mul_f32 v[34:35], v[44:45], v[38:39]
	s_waitcnt vmcnt(0)
	v_pk_mul_f32 v[36:37], v[46:47], v[52:53]
	v_pk_mul_f32 v[38:39], v[48:49], v[50:51]
	s_nop 1
	v_mov_b32_dpp v228, v36 row_ror:8 row_mask:0xf bank_mask:0xf
	v_mov_b32_dpp v229, v37 row_ror:8 row_mask:0xf bank_mask:0xf
	v_mov_b32_dpp v230, v38 row_ror:8 row_mask:0xf bank_mask:0xf
	v_mov_b32_dpp v231, v39 row_ror:8 row_mask:0xf bank_mask:0xf
	v_cndmask_b32_e64 v36, v228, v32, s[98:99]
	v_cndmask_b32_e64 v37, v229, v33, s[98:99]
	v_cndmask_b32_e64 v38, v230, v34, s[98:99]
	v_cndmask_b32_e64 v39, v231, v35, s[98:99]
	v_cndmask_b32_e64 v228, v32, v228, s[98:99]
	v_cndmask_b32_e64 v229, v33, v229, s[98:99]
	v_cndmask_b32_e64 v230, v34, v230, s[98:99]
	v_cndmask_b32_e64 v231, v35, v231, s[98:99]
	v_lshl_add_u64 v[232:233], v[56:57], 0, v[236:237]
	v_lshl_add_u64 v[234:235], v[56:57], 0, v[238:239]
	global_store_dwordx4 v[232:233], v[36:39], off offset:512
	global_store_dwordx4 v[234:235], v[228:231], off offset:512
	global_load_dword v42, v[112:113], off offset:640 sc1
	s_nop 0
	global_load_dwordx4 v[32:35], v[140:141], off
	global_load_dwordx4 v[36:39], v[140:141], off offset:16
	s_waitcnt vmcnt(2)
	v_fmamk_f32 v42, v42, 0x3a800000, v137
	v_mul_f32_e32 v43, 0x4b800000, v42
	v_cmp_gt_f32_e32 vcc, s0, v42
	s_nop 1
	v_cndmask_b32_e32 v42, v42, v43, vcc
	v_rsq_f32_e32 v42, v42
	s_nop 0
	v_mul_f32_e32 v43, 0x45800000, v42
	v_cndmask_b32_e32 v42, v42, v43, vcc
	v_pk_mul_f32 v[44:45], v[164:165], v[42:43] op_sel_hi:[1,0]
	v_pk_mul_f32 v[30:31], v[30:31], v[42:43] op_sel_hi:[1,0]
	v_pk_mul_f32 v[46:47], v[28:29], v[42:43] op_sel_hi:[1,0]
	v_pk_mul_f32 v[48:49], v[26:27], v[42:43] op_sel_hi:[1,0]
	s_waitcnt vmcnt(1)
	v_pk_mul_f32 v[28:29], v[34:35], v[30:31]
	v_pk_mul_f32 v[26:27], v[32:33], v[44:45]
	s_waitcnt vmcnt(0)
;     __device__ __forceinline__ void operator()(f32x4 (&acc)[2][2][4][2], const pg8::Unit& u, int wr, int wc, int fr, int fq) const {
;     ...
; #pragma unroll
;         for (int ai = 0; ai < 2; ++ai)
; #pragma unroll
;             for (int m = 0; m < 4; ++m) {
;                 const int row = row0 + ai * 128 + m * 16;
;                 const float rstd = rsqrtf(__hip_atomic_load(rowss + row, __ATOMIC_RELAXED, __HIP_MEMORY_SCOPE_AGENT) * (1.f / 1024.f) + EPS);
; #pragma unroll
;                 for (int bj = 0; bj < 2; ++bj) {
;                     const int c = col0 + bj * 128;
;                     const f32x4 w0 = *(const f32x4*)(nw + c), w1 = *(const f32x4*)(nw + c + 4);
;                     float* op = out + (size_t)row * D + c;
;                     *(f32x4*)op = acc[ai][bj][m][0] * rstd * w0; *(f32x4*)(op + 4) = acc[ai][bj][m][1] * rstd * w1;
;                 }
;             }
	v_pk_mul_f32 v[32:33], v[38:39], v[48:49]
	v_pk_mul_f32 v[30:31], v[36:37], v[46:47]
	s_nop 1
	v_mov_b32_dpp v228, v30 row_ror:8 row_mask:0xf bank_mask:0xf
	v_mov_b32_dpp v229, v31 row_ror:8 row_mask:0xf bank_mask:0xf
	v_mov_b32_dpp v230, v32 row_ror:8 row_mask:0xf bank_mask:0xf
	v_mov_b32_dpp v231, v33 row_ror:8 row_mask:0xf bank_mask:0xf
	v_cndmask_b32_e64 v30, v228, v26, s[98:99]
	v_cndmask_b32_e64 v31, v229, v27, s[98:99]
	v_cndmask_b32_e64 v32, v230, v28, s[98:99]
	v_cndmask_b32_e64 v33, v231, v29, s[98:99]
	v_cndmask_b32_e64 v228, v26, v228, s[98:99]
	v_cndmask_b32_e64 v229, v27, v229, s[98:99]
	v_cndmask_b32_e64 v230, v28, v230, s[98:99]
	v_cndmask_b32_e64 v231, v29, v231, s[98:99]
	v_lshl_add_u64 v[232:233], v[40:41], 0, v[236:237]
	v_lshl_add_u64 v[234:235], v[40:41], 0, v[238:239]
	global_store_dwordx4 v[232:233], v[30:33], off
	global_store_dwordx4 v[234:235], v[228:231], off
	global_load_dwordx4 v[26:29], v[140:141], off offset:512
	s_nop 0
	global_load_dwordx4 v[30:33], v[140:141], off offset:528
	v_pk_mul_f32 v[22:23], v[22:23], v[42:43] op_sel_hi:[1,0]
	v_pk_mul_f32 v[20:21], v[20:21], v[42:43] op_sel_hi:[1,0]
	v_pk_mul_f32 v[34:35], v[18:19], v[42:43] op_sel_hi:[1,0]
	v_pk_mul_f32 v[36:37], v[16:17], v[42:43] op_sel_hi:[1,0]
	s_waitcnt vmcnt(1)
	v_pk_mul_f32 v[16:17], v[26:27], v[20:21]
	v_pk_mul_f32 v[18:19], v[28:29], v[22:23]
	s_waitcnt vmcnt(0)
	v_pk_mul_f32 v[20:21], v[30:31], v[36:37]
	v_pk_mul_f32 v[22:23], v[32:33], v[34:35]
	s_nop 1
	v_mov_b32_dpp v228, v20 row_ror:8 row_mask:0xf bank_mask:0xf
	v_mov_b32_dpp v229, v21 row_ror:8 row_mask:0xf bank_mask:0xf
	v_mov_b32_dpp v230, v22 row_ror:8 row_mask:0xf bank_mask:0xf
	v_mov_b32_dpp v231, v23 row_ror:8 row_mask:0xf bank_mask:0xf
	v_cndmask_b32_e64 v20, v228, v16, s[98:99]
	v_cndmask_b32_e64 v21, v229, v17, s[98:99]
	v_cndmask_b32_e64 v22, v230, v18, s[98:99]
	v_cndmask_b32_e64 v23, v231, v19, s[98:99]
	v_cndmask_b32_e64 v228, v16, v228, s[98:99]
	v_cndmask_b32_e64 v229, v17, v229, s[98:99]
	v_cndmask_b32_e64 v230, v18, v230, s[98:99]
	v_cndmask_b32_e64 v231, v19, v231, s[98:99]
	v_lshl_add_u64 v[232:233], v[40:41], 0, v[236:237]
	v_lshl_add_u64 v[234:235], v[40:41], 0, v[238:239]
	global_store_dwordx4 v[232:233], v[20:23], off offset:512
	global_store_dwordx4 v[234:235], v[228:231], off offset:512
	global_load_dword v26, v[112:113], off offset:704 sc1
	s_nop 0
	global_load_dwordx4 v[16:19], v[140:141], off
	global_load_dwordx4 v[20:23], v[140:141], off offset:16
	s_waitcnt vmcnt(2)
	v_fmac_f32_e32 v137, 0x3a800000, v26
	v_mul_f32_e32 v26, 0x4b800000, v137
	v_cmp_gt_f32_e32 vcc, s0, v137
	s_nop 1
	v_cndmask_b32_e32 v26, v137, v26, vcc
	v_rsq_f32_e32 v26, v26
	s_nop 0
	v_mul_f32_e32 v27, 0x45800000, v26
	v_cndmask_b32_e32 v26, v26, v27, vcc
	v_pk_mul_f32 v[12:13], v[12:13], v[26:27] op_sel_hi:[1,0]
	v_pk_mul_f32 v[14:15], v[14:15], v[26:27] op_sel_hi:[1,0]
	v_pk_mul_f32 v[28:29], v[8:9], v[26:27] op_sel_hi:[1,0]
	v_pk_mul_f32 v[30:31], v[10:11], v[26:27] op_sel_hi:[1,0]
	s_waitcnt vmcnt(1)
	v_pk_mul_f32 v[10:11], v[18:19], v[14:15]
	v_pk_mul_f32 v[8:9], v[16:17], v[12:13]
	s_waitcnt vmcnt(0)
	v_pk_mul_f32 v[14:15], v[22:23], v[30:31]
	v_pk_mul_f32 v[12:13], v[20:21], v[28:29]
	s_nop 1
	v_mov_b32_dpp v228, v12 row_ror:8 row_mask:0xf bank_mask:0xf
	v_mov_b32_dpp v229, v13 row_ror:8 row_mask:0xf bank_mask:0xf
	v_mov_b32_dpp v230, v14 row_ror:8 row_mask:0xf bank_mask:0xf
	v_mov_b32_dpp v231, v15 row_ror:8 row_mask:0xf bank_mask:0xf
	v_cndmask_b32_e64 v12, v228, v8, s[98:99]
	v_cndmask_b32_e64 v13, v229, v9, s[98:99]
	v_cndmask_b32_e64 v14, v230, v10, s[98:99]
	v_cndmask_b32_e64 v15, v231, v11, s[98:99]
	v_cndmask_b32_e64 v228, v8, v228, s[98:99]
	v_cndmask_b32_e64 v229, v9, v229, s[98:99]
	v_cndmask_b32_e64 v230, v10, v230, s[98:99]
	v_cndmask_b32_e64 v231, v11, v231, s[98:99]
	v_lshl_add_u64 v[232:233], v[24:25], 0, v[236:237]
	v_lshl_add_u64 v[234:235], v[24:25], 0, v[238:239]
	global_store_dwordx4 v[232:233], v[12:15], off
	global_store_dwordx4 v[234:235], v[228:231], off
	global_load_dwordx4 v[8:11], v[140:141], off offset:512
	s_nop 0
	global_load_dwordx4 v[12:15], v[140:141], off offset:528
	v_pk_mul_f32 v[6:7], v[6:7], v[26:27] op_sel_hi:[1,0]
	v_pk_mul_f32 v[4:5], v[4:5], v[26:27] op_sel_hi:[1,0]
	v_pk_mul_f32 v[16:17], v[2:3], v[26:27] op_sel_hi:[1,0]
	v_pk_mul_f32 v[18:19], v[0:1], v[26:27] op_sel_hi:[1,0]
	s_waitcnt vmcnt(1)
	v_pk_mul_f32 v[0:1], v[8:9], v[4:5]
	v_pk_mul_f32 v[2:3], v[10:11], v[6:7]
	s_waitcnt vmcnt(0)
	v_pk_mul_f32 v[4:5], v[12:13], v[18:19]
	v_pk_mul_f32 v[6:7], v[14:15], v[16:17]
	s_nop 1
	v_mov_b32_dpp v228, v4 row_ror:8 row_mask:0xf bank_mask:0xf
	v_mov_b32_dpp v229, v5 row_ror:8 row_mask:0xf bank_mask:0xf
	v_mov_b32_dpp v230, v6 row_ror:8 row_mask:0xf bank_mask:0xf
	v_mov_b32_dpp v231, v7 row_ror:8 row_mask:0xf bank_mask:0xf
	v_cndmask_b32_e64 v4, v228, v0, s[98:99]
	v_cndmask_b32_e64 v5, v229, v1, s[98:99]
	v_cndmask_b32_e64 v6, v230, v2, s[98:99]
	v_cndmask_b32_e64 v7, v231, v3, s[98:99]
	v_cndmask_b32_e64 v228, v0, v228, s[98:99]
	v_cndmask_b32_e64 v229, v1, v229, s[98:99]
	v_cndmask_b32_e64 v230, v2, v230, s[98:99]
	v_cndmask_b32_e64 v231, v3, v231, s[98:99]
	v_lshl_add_u64 v[232:233], v[24:25], 0, v[236:237]
	v_lshl_add_u64 v[234:235], v[24:25], 0, v[238:239]
	global_store_dwordx4 v[232:233], v[4:7], off offset:512
	global_store_dwordx4 v[234:235], v[228:231], off offset:512
